# FF1 output stores: nt plus sc1
# baseline (speedup 1.0000x reference)
; DI unsigned pack2(float a, float b) { f32x2_t v = {a, b}; bf16x2_t r = __builtin_convertvector(v, bf16x2_t); return __builtin_bit_cast(unsigned, r); }
; DI bfu* wsb(const PX& p, size_t off) { return (bfu*)(p.ws + off); }
; template <int EPI, int HM>
; DI void epi256(const PX& p, int l, f32x4 (&acc)[2][2][4][2], int brow, int bcol, int aux, bool src_input) {
;     ...
; #pragma unroll
;   for (int ai = 0; ai < (HM ? 1 : 2); ai++)
; #pragma unroll
;     for (int bj = 0; bj < 2; bj++)
; #pragma unroll
;       for (int m = 0; m < 4; m++) {
;           const int row = brow + ai * 128 + wr * 64 + m * 16 + fr;
;           const int col0 = bcol + bj * 128 + wc * 32 + fq * 8;
;     ...
;           } else if (EPI == EPI_FF1) {
;             float t[8];
; #pragma unroll
;             for (int j = 0; j < 8; j++) { t[j] = fmaxf(v[j], 0.f); t[j] *= t[j]; }
;             uint4 o; o.x = pack2(t[0], t[1]); o.y = pack2(t[2], t[3]); o.z = pack2(t[4], t[5]); o.w = pack2(t[6], t[7]);
;             *(uint4*)(wsb(p, OFF_BIG) + (size_t)row * 8192 + col0) = o;
.LBB0_72:
	v_mov_b32_e32 v0, v188
	v_readlane_b32 s8, v253, 29
	v_ashrrev_i32_e32 v131, 2, v0
	v_and_b32_e32 v130, 15, v0
	v_and_b32_e32 v131, 0xffffffc0, v131
	v_lshrrev_b32_e32 v0, 1, v0
	v_add3_u32 v130, v130, s16, v131
	v_and_b32_e32 v131, 0x60, v0
	v_and_b32_e32 v0, 24, v0
	v_add3_u32 v132, v131, s14, v0
	v_max_f32_e32 v0, v126, v126
	v_max_f32_e32 v126, 0, v0
	v_max_f32_e32 v0, v127, v127
	v_max_f32_e32 v127, 0, v0
	v_max_f32_e32 v0, v128, v128
	v_max_f32_e32 v128, 0, v0
	v_max_f32_e32 v0, v129, v129
	v_max_f32_e32 v129, 0, v0
	v_max_f32_e32 v0, v122, v122
	v_max_f32_e32 v122, 0, v0
	v_max_f32_e32 v0, v123, v123
	v_max_f32_e32 v123, 0, v0
	v_max_f32_e32 v0, v124, v124
	v_max_f32_e32 v124, 0, v0
	v_max_f32_e32 v0, v125, v125
	v_max_f32_e32 v125, 0, v0
	v_max_f32_e32 v0, v118, v118
	v_max_f32_e32 v118, 0, v0
	v_max_f32_e32 v0, v119, v119
	v_max_f32_e32 v119, 0, v0
	v_max_f32_e32 v0, v120, v120
	v_pk_mul_f32 v[126:127], v[126:127], v[126:127]
	v_pk_mul_f32 v[122:123], v[122:123], v[122:123]
	v_ashrrev_i32_e32 v131, 31, v130
	v_max_f32_e32 v120, 0, v0
	v_max_f32_e32 v0, v121, v121
	v_ashrrev_i32_e32 v133, 31, v132
	v_pk_mul_f32 v[128:129], v[128:129], v[128:129]
	v_pk_mul_f32 v[134:135], v[124:125], v[124:125]
	v_cvt_pk_bf16_f32 v124, v126, v127
	v_cvt_pk_bf16_f32 v126, v122, v123
	v_lshlrev_b64 v[122:123], 14, v[130:131]
	v_readlane_b32 s9, v253, 30
	v_max_f32_e32 v121, 0, v0
	v_max_f32_e32 v0, v114, v114
	v_cvt_pk_bf16_f32 v125, v128, v129
	v_lshl_add_u64 v[128:129], s[8:9], 0, v[122:123]
	v_lshlrev_b64 v[122:123], 1, v[132:133]
	v_max_f32_e32 v114, 0, v0
	v_max_f32_e32 v0, v115, v115
	v_cvt_pk_bf16_f32 v127, v134, v135
	v_lshl_add_u64 v[128:129], v[128:129], 0, v[122:123]
	v_max_f32_e32 v115, 0, v0
	v_max_f32_e32 v0, v116, v116
	global_store_dwordx4 v[128:129], v[124:127], off nt sc1
	v_add_u32_e32 v132, 16, v130
	v_pk_mul_f32 v[118:119], v[118:119], v[118:119]
	v_pk_mul_f32 v[124:125], v[114:115], v[114:115]
	v_max_f32_e32 v114, 0, v0
	v_max_f32_e32 v0, v117, v117
	v_max_f32_e32 v115, 0, v0
	v_max_f32_e32 v0, v110, v110
	v_max_f32_e32 v110, 0, v0
	v_max_f32_e32 v0, v111, v111
	v_max_f32_e32 v111, 0, v0
	v_max_f32_e32 v0, v112, v112
	v_ashrrev_i32_e32 v133, 31, v132
	v_max_f32_e32 v112, 0, v0
	v_max_f32_e32 v0, v113, v113
	v_pk_mul_f32 v[126:127], v[114:115], v[114:115]
	v_cvt_pk_bf16_f32 v114, v118, v119
	v_lshlrev_b64 v[118:119], 14, v[132:133]
	v_max_f32_e32 v113, 0, v0
	v_max_f32_e32 v0, v106, v106
	v_pk_mul_f32 v[120:121], v[120:121], v[120:121]
	v_lshl_add_u64 v[118:119], s[8:9], 0, v[118:119]
	v_max_f32_e32 v106, 0, v0
	v_max_f32_e32 v0, v107, v107
	v_cvt_pk_bf16_f32 v115, v120, v121
	v_cvt_pk_bf16_f32 v116, v124, v125
	v_cvt_pk_bf16_f32 v117, v126, v127
	v_lshl_add_u64 v[118:119], v[118:119], 0, v[122:123]
	v_max_f32_e32 v107, 0, v0
	v_max_f32_e32 v0, v108, v108
	global_store_dwordx4 v[118:119], v[114:117], off nt sc1
	v_add_u32_e32 v120, 32, v130
	v_pk_mul_f32 v[110:111], v[110:111], v[110:111]
	v_pk_mul_f32 v[114:115], v[106:107], v[106:107]
	v_max_f32_e32 v106, 0, v0
	v_max_f32_e32 v0, v109, v109
	v_max_f32_e32 v107, 0, v0
	v_max_f32_e32 v0, v102, v102
	v_max_f32_e32 v102, 0, v0
	v_max_f32_e32 v0, v103, v103
	v_max_f32_e32 v103, 0, v0
	v_max_f32_e32 v0, v104, v104
	v_ashrrev_i32_e32 v121, 31, v120
	v_max_f32_e32 v104, 0, v0
	v_max_f32_e32 v0, v105, v105
	v_pk_mul_f32 v[116:117], v[106:107], v[106:107]
	v_cvt_pk_bf16_f32 v106, v110, v111
	v_lshlrev_b64 v[110:111], 14, v[120:121]
	v_max_f32_e32 v105, 0, v0
	v_max_f32_e32 v0, v98, v98
	v_pk_mul_f32 v[112:113], v[112:113], v[112:113]
	v_lshl_add_u64 v[110:111], s[8:9], 0, v[110:111]
	v_max_f32_e32 v98, 0, v0
	v_max_f32_e32 v0, v99, v99
	v_cvt_pk_bf16_f32 v107, v112, v113
	v_cvt_pk_bf16_f32 v108, v114, v115
	v_cvt_pk_bf16_f32 v109, v116, v117
	v_lshl_add_u64 v[110:111], v[110:111], 0, v[122:123]
	v_max_f32_e32 v99, 0, v0
	v_max_f32_e32 v0, v100, v100
	global_store_dwordx4 v[110:111], v[106:109], off nt sc1
	v_add_u32_e32 v112, 48, v130
	v_pk_mul_f32 v[102:103], v[102:103], v[102:103]
	v_pk_mul_f32 v[106:107], v[98:99], v[98:99]
	v_max_f32_e32 v98, 0, v0
	v_max_f32_e32 v0, v101, v101
	v_max_f32_e32 v99, 0, v0
	v_max_f32_e32 v0, v94, v94
	v_max_f32_e32 v94, 0, v0
	v_max_f32_e32 v0, v95, v95
	v_max_f32_e32 v95, 0, v0
	v_max_f32_e32 v0, v96, v96
	v_ashrrev_i32_e32 v113, 31, v112
	v_max_f32_e32 v96, 0, v0
	v_max_f32_e32 v0, v97, v97
	v_pk_mul_f32 v[108:109], v[98:99], v[98:99]
	v_cvt_pk_bf16_f32 v98, v102, v103
	v_lshlrev_b64 v[102:103], 14, v[112:113]
	v_max_f32_e32 v97, 0, v0
	v_max_f32_e32 v0, v90, v90
	v_pk_mul_f32 v[104:105], v[104:105], v[104:105]
	v_lshl_add_u64 v[102:103], s[8:9], 0, v[102:103]
	v_max_f32_e32 v90, 0, v0
	v_max_f32_e32 v0, v91, v91
	v_cvt_pk_bf16_f32 v99, v104, v105
	v_cvt_pk_bf16_f32 v100, v106, v107
	v_cvt_pk_bf16_f32 v101, v108, v109
	v_lshl_add_u64 v[102:103], v[102:103], 0, v[122:123]
	v_max_f32_e32 v91, 0, v0
	v_max_f32_e32 v0, v92, v92
	global_store_dwordx4 v[102:103], v[98:101], off nt sc1
	v_pk_mul_f32 v[94:95], v[94:95], v[94:95]
	v_pk_mul_f32 v[96:97], v[96:97], v[96:97]
	v_pk_mul_f32 v[98:99], v[90:91], v[90:91]
	v_max_f32_e32 v90, 0, v0
	v_max_f32_e32 v0, v93, v93
	v_max_f32_e32 v91, 0, v0
	v_max_f32_e32 v0, v86, v86
	v_max_f32_e32 v86, 0, v0
	v_max_f32_e32 v0, v87, v87
	v_max_f32_e32 v87, 0, v0
	v_max_f32_e32 v0, v88, v88
	v_max_f32_e32 v88, 0, v0
	v_max_f32_e32 v0, v89, v89
	v_max_f32_e32 v89, 0, v0
	v_max_f32_e32 v0, v82, v82
	v_pk_mul_f32 v[100:101], v[90:91], v[90:91]
	v_max_f32_e32 v82, 0, v0
	v_max_f32_e32 v0, v83, v83
	v_cvt_pk_bf16_f32 v90, v94, v95
	v_cvt_pk_bf16_f32 v91, v96, v97
	v_cvt_pk_bf16_f32 v92, v98, v99
	v_cvt_pk_bf16_f32 v93, v100, v101
; DI unsigned pack2(float a, float b) { f32x2_t v = {a, b}; bf16x2_t r = __builtin_convertvector(v, bf16x2_t); return __builtin_bit_cast(unsigned, r); }
; DI bfu* wsb(const PX& p, size_t off) { return (bfu*)(p.ws + off); }
; template <int EPI, int HM>
; DI void epi256(const PX& p, int l, f32x4 (&acc)[2][2][4][2], int brow, int bcol, int aux, bool src_input) {
;     ...
;           } else if (EPI == EPI_FF1) {
;             float t[8];
; #pragma unroll
;             for (int j = 0; j < 8; j++) { t[j] = fmaxf(v[j], 0.f); t[j] *= t[j]; }
;             uint4 o; o.x = pack2(t[0], t[1]); o.y = pack2(t[2], t[3]); o.z = pack2(t[4], t[5]); o.w = pack2(t[6], t[7]);
;             *(uint4*)(wsb(p, OFF_BIG) + (size_t)row * 8192 + col0) = o;
	v_max_f32_e32 v83, 0, v0
	v_max_f32_e32 v0, v84, v84
	global_store_dwordx4 v[128:129], v[90:93], off offset:256 nt sc1
	v_pk_mul_f32 v[86:87], v[86:87], v[86:87]
	v_pk_mul_f32 v[88:89], v[88:89], v[88:89]
	v_pk_mul_f32 v[90:91], v[82:83], v[82:83]
	v_max_f32_e32 v82, 0, v0
	v_max_f32_e32 v0, v85, v85
	v_max_f32_e32 v83, 0, v0
	v_max_f32_e32 v0, v78, v78
	v_max_f32_e32 v78, 0, v0
	v_max_f32_e32 v0, v79, v79
	v_max_f32_e32 v79, 0, v0
	v_max_f32_e32 v0, v80, v80
	v_max_f32_e32 v80, 0, v0
	v_max_f32_e32 v0, v81, v81
	v_max_f32_e32 v81, 0, v0
	v_max_f32_e32 v0, v74, v74
	v_pk_mul_f32 v[92:93], v[82:83], v[82:83]
	v_max_f32_e32 v74, 0, v0
	v_max_f32_e32 v0, v75, v75
	v_cvt_pk_bf16_f32 v82, v86, v87
	v_cvt_pk_bf16_f32 v83, v88, v89
	v_cvt_pk_bf16_f32 v84, v90, v91
	v_cvt_pk_bf16_f32 v85, v92, v93
	v_max_f32_e32 v75, 0, v0
	v_max_f32_e32 v0, v76, v76
	global_store_dwordx4 v[118:119], v[82:85], off offset:256 nt sc1
	v_pk_mul_f32 v[78:79], v[78:79], v[78:79]
	v_pk_mul_f32 v[80:81], v[80:81], v[80:81]
	v_pk_mul_f32 v[82:83], v[74:75], v[74:75]
	v_max_f32_e32 v74, 0, v0
	v_max_f32_e32 v0, v77, v77
	v_max_f32_e32 v75, 0, v0
	v_max_f32_e32 v0, v70, v70
	v_max_f32_e32 v70, 0, v0
	v_max_f32_e32 v0, v71, v71
	v_max_f32_e32 v71, 0, v0
	v_max_f32_e32 v0, v72, v72
	v_max_f32_e32 v72, 0, v0
	v_max_f32_e32 v0, v73, v73
	v_max_f32_e32 v73, 0, v0
	v_max_f32_e32 v0, v66, v66
	v_pk_mul_f32 v[84:85], v[74:75], v[74:75]
	v_max_f32_e32 v66, 0, v0
	v_max_f32_e32 v0, v67, v67
	v_cvt_pk_bf16_f32 v74, v78, v79
	v_cvt_pk_bf16_f32 v75, v80, v81
	v_cvt_pk_bf16_f32 v76, v82, v83
	v_cvt_pk_bf16_f32 v77, v84, v85
	v_max_f32_e32 v67, 0, v0
	v_max_f32_e32 v0, v68, v68
	global_store_dwordx4 v[110:111], v[74:77], off offset:256 nt sc1
	v_pk_mul_f32 v[70:71], v[70:71], v[70:71]
	v_pk_mul_f32 v[72:73], v[72:73], v[72:73]
	v_pk_mul_f32 v[74:75], v[66:67], v[66:67]
	v_max_f32_e32 v66, 0, v0
	v_max_f32_e32 v0, v69, v69
	v_max_f32_e32 v67, 0, v0
	v_max_f32_e32 v0, v62, v62
	v_max_f32_e32 v62, 0, v0
	v_max_f32_e32 v0, v63, v63
	v_max_f32_e32 v63, 0, v0
	v_max_f32_e32 v0, v64, v64
	v_max_f32_e32 v64, 0, v0
	v_max_f32_e32 v0, v65, v65
	v_max_f32_e32 v65, 0, v0
	v_max_f32_e32 v0, v58, v58
	v_pk_mul_f32 v[76:77], v[66:67], v[66:67]
	v_max_f32_e32 v58, 0, v0
	v_max_f32_e32 v0, v59, v59
	v_cvt_pk_bf16_f32 v66, v70, v71
	v_cvt_pk_bf16_f32 v67, v72, v73
	v_cvt_pk_bf16_f32 v68, v74, v75
	v_cvt_pk_bf16_f32 v69, v76, v77
	v_max_f32_e32 v59, 0, v0
	v_max_f32_e32 v0, v60, v60
	global_store_dwordx4 v[102:103], v[66:69], off offset:256 nt sc1
	v_pk_mul_f32 v[62:63], v[62:63], v[62:63]
	v_pk_mul_f32 v[64:65], v[64:65], v[64:65]
	v_pk_mul_f32 v[68:69], v[58:59], v[58:59]
	v_max_f32_e32 v58, 0, v0
	v_max_f32_e32 v0, v61, v61
	v_max_f32_e32 v59, 0, v0
	v_max_f32_e32 v0, v54, v54
	v_max_f32_e32 v54, 0, v0
	v_max_f32_e32 v0, v55, v55
	v_add_u32_e32 v66, 0x80, v130
	v_max_f32_e32 v55, 0, v0
	v_max_f32_e32 v0, v56, v56
	v_ashrrev_i32_e32 v67, 31, v66
	v_max_f32_e32 v56, 0, v0
	v_max_f32_e32 v0, v57, v57
	v_pk_mul_f32 v[70:71], v[58:59], v[58:59]
	v_cvt_pk_bf16_f32 v58, v62, v63
	v_lshlrev_b64 v[62:63], 14, v[66:67]
	v_max_f32_e32 v57, 0, v0
	v_max_f32_e32 v0, v50, v50
	v_lshl_add_u64 v[62:63], s[8:9], 0, v[62:63]
	v_max_f32_e32 v50, 0, v0
	v_max_f32_e32 v0, v51, v51
	v_cvt_pk_bf16_f32 v59, v64, v65
	v_cvt_pk_bf16_f32 v60, v68, v69
	v_cvt_pk_bf16_f32 v61, v70, v71
	v_lshl_add_u64 v[62:63], v[62:63], 0, v[122:123]
	v_max_f32_e32 v51, 0, v0
	v_max_f32_e32 v0, v52, v52
	global_store_dwordx4 v[62:63], v[58:61], off nt sc1
	v_add_u32_e32 v64, 0x90, v130
	v_pk_mul_f32 v[54:55], v[54:55], v[54:55]
	v_pk_mul_f32 v[58:59], v[50:51], v[50:51]
	v_max_f32_e32 v50, 0, v0
	v_max_f32_e32 v0, v53, v53
	v_max_f32_e32 v51, 0, v0
	v_max_f32_e32 v0, v46, v46
	v_max_f32_e32 v46, 0, v0
	v_max_f32_e32 v0, v47, v47
	v_max_f32_e32 v47, 0, v0
	v_max_f32_e32 v0, v48, v48
	v_ashrrev_i32_e32 v65, 31, v64
	v_max_f32_e32 v48, 0, v0
	v_max_f32_e32 v0, v49, v49
	v_pk_mul_f32 v[60:61], v[50:51], v[50:51]
	v_cvt_pk_bf16_f32 v50, v54, v55
	v_lshlrev_b64 v[54:55], 14, v[64:65]
	v_max_f32_e32 v49, 0, v0
	v_max_f32_e32 v0, v42, v42
	v_pk_mul_f32 v[56:57], v[56:57], v[56:57]
	v_lshl_add_u64 v[54:55], s[8:9], 0, v[54:55]
	v_max_f32_e32 v42, 0, v0
	v_max_f32_e32 v0, v43, v43
	v_cvt_pk_bf16_f32 v51, v56, v57
	v_cvt_pk_bf16_f32 v52, v58, v59
	v_cvt_pk_bf16_f32 v53, v60, v61
	v_lshl_add_u64 v[54:55], v[54:55], 0, v[122:123]
	v_max_f32_e32 v43, 0, v0
	v_max_f32_e32 v0, v44, v44
	global_store_dwordx4 v[54:55], v[50:53], off nt sc1
	v_add_u32_e32 v56, 0xa0, v130
	v_pk_mul_f32 v[46:47], v[46:47], v[46:47]
	v_pk_mul_f32 v[50:51], v[42:43], v[42:43]
	v_max_f32_e32 v42, 0, v0
	v_max_f32_e32 v0, v45, v45
; DI unsigned pack2(float a, float b) { f32x2_t v = {a, b}; bf16x2_t r = __builtin_convertvector(v, bf16x2_t); return __builtin_bit_cast(unsigned, r); }
; DI bfu* wsb(const PX& p, size_t off) { return (bfu*)(p.ws + off); }
; template <int EPI, int HM>
; DI void epi256(const PX& p, int l, f32x4 (&acc)[2][2][4][2], int brow, int bcol, int aux, bool src_input) {
;     ...
;           } else if (EPI == EPI_FF1) {
;             float t[8];
; #pragma unroll
;             for (int j = 0; j < 8; j++) { t[j] = fmaxf(v[j], 0.f); t[j] *= t[j]; }
;             uint4 o; o.x = pack2(t[0], t[1]); o.y = pack2(t[2], t[3]); o.z = pack2(t[4], t[5]); o.w = pack2(t[6], t[7]);
;             *(uint4*)(wsb(p, OFF_BIG) + (size_t)row * 8192 + col0) = o;
	v_max_f32_e32 v43, 0, v0
	v_max_f32_e32 v0, v38, v38
	v_max_f32_e32 v38, 0, v0
	v_max_f32_e32 v0, v39, v39
	v_max_f32_e32 v39, 0, v0
	v_max_f32_e32 v0, v40, v40
	v_ashrrev_i32_e32 v57, 31, v56
	v_max_f32_e32 v40, 0, v0
	v_max_f32_e32 v0, v41, v41
	v_pk_mul_f32 v[52:53], v[42:43], v[42:43]
	v_cvt_pk_bf16_f32 v42, v46, v47
	v_lshlrev_b64 v[46:47], 14, v[56:57]
	v_max_f32_e32 v41, 0, v0
	v_max_f32_e32 v0, v34, v34
	v_pk_mul_f32 v[48:49], v[48:49], v[48:49]
	v_lshl_add_u64 v[46:47], s[8:9], 0, v[46:47]
	v_max_f32_e32 v34, 0, v0
	v_max_f32_e32 v0, v35, v35
	v_cvt_pk_bf16_f32 v43, v48, v49
	v_cvt_pk_bf16_f32 v44, v50, v51
	v_cvt_pk_bf16_f32 v45, v52, v53
	v_lshl_add_u64 v[46:47], v[46:47], 0, v[122:123]
	v_max_f32_e32 v35, 0, v0
	v_max_f32_e32 v0, v36, v36
	global_store_dwordx4 v[46:47], v[42:45], off nt sc1
	v_add_u32_e32 v48, 0xb0, v130
	v_pk_mul_f32 v[38:39], v[38:39], v[38:39]
	v_pk_mul_f32 v[42:43], v[34:35], v[34:35]
	v_max_f32_e32 v34, 0, v0
	v_max_f32_e32 v0, v37, v37
	v_max_f32_e32 v35, 0, v0
	v_max_f32_e32 v0, v30, v30
	v_max_f32_e32 v30, 0, v0
	v_max_f32_e32 v0, v31, v31
	v_max_f32_e32 v31, 0, v0
	v_max_f32_e32 v0, v32, v32
	v_ashrrev_i32_e32 v49, 31, v48
	v_max_f32_e32 v32, 0, v0
	v_max_f32_e32 v0, v33, v33
	v_pk_mul_f32 v[44:45], v[34:35], v[34:35]
	v_cvt_pk_bf16_f32 v34, v38, v39
	v_lshlrev_b64 v[38:39], 14, v[48:49]
	v_max_f32_e32 v33, 0, v0
	v_max_f32_e32 v0, v26, v26
	v_pk_mul_f32 v[40:41], v[40:41], v[40:41]
	v_lshl_add_u64 v[38:39], s[8:9], 0, v[38:39]
	v_max_f32_e32 v26, 0, v0
	v_max_f32_e32 v0, v27, v27
	v_cvt_pk_bf16_f32 v35, v40, v41
	v_cvt_pk_bf16_f32 v36, v42, v43
	v_cvt_pk_bf16_f32 v37, v44, v45
	v_lshl_add_u64 v[38:39], v[38:39], 0, v[122:123]
	v_max_f32_e32 v27, 0, v0
	v_max_f32_e32 v0, v28, v28
	global_store_dwordx4 v[38:39], v[34:37], off nt sc1
	v_pk_mul_f32 v[30:31], v[30:31], v[30:31]
	v_pk_mul_f32 v[32:33], v[32:33], v[32:33]
	v_pk_mul_f32 v[34:35], v[26:27], v[26:27]
	v_max_f32_e32 v26, 0, v0
	v_max_f32_e32 v0, v29, v29
	v_max_f32_e32 v27, 0, v0
	v_max_f32_e32 v0, v22, v22
	v_max_f32_e32 v22, 0, v0
	v_max_f32_e32 v0, v23, v23
	v_max_f32_e32 v23, 0, v0
	v_max_f32_e32 v0, v24, v24
	v_max_f32_e32 v24, 0, v0
	v_max_f32_e32 v0, v25, v25
	v_max_f32_e32 v25, 0, v0
	v_max_f32_e32 v0, v18, v18
	v_pk_mul_f32 v[36:37], v[26:27], v[26:27]
	v_max_f32_e32 v18, 0, v0
	v_max_f32_e32 v0, v19, v19
	v_cvt_pk_bf16_f32 v26, v30, v31
	v_cvt_pk_bf16_f32 v27, v32, v33
	v_cvt_pk_bf16_f32 v28, v34, v35
	v_cvt_pk_bf16_f32 v29, v36, v37
	v_max_f32_e32 v19, 0, v0
	v_max_f32_e32 v0, v20, v20
	global_store_dwordx4 v[62:63], v[26:29], off offset:256 nt sc1
	v_pk_mul_f32 v[22:23], v[22:23], v[22:23]
	v_pk_mul_f32 v[24:25], v[24:25], v[24:25]
	v_pk_mul_f32 v[26:27], v[18:19], v[18:19]
	v_max_f32_e32 v18, 0, v0
	v_max_f32_e32 v0, v21, v21
	v_max_f32_e32 v19, 0, v0
	v_max_f32_e32 v0, v14, v14
	v_max_f32_e32 v14, 0, v0
	v_max_f32_e32 v0, v15, v15
	v_max_f32_e32 v15, 0, v0
	v_max_f32_e32 v0, v16, v16
	v_max_f32_e32 v16, 0, v0
	v_max_f32_e32 v0, v17, v17
	v_max_f32_e32 v17, 0, v0
	v_max_f32_e32 v0, v10, v10
	v_pk_mul_f32 v[28:29], v[18:19], v[18:19]
	v_max_f32_e32 v10, 0, v0
	v_max_f32_e32 v0, v11, v11
	v_cvt_pk_bf16_f32 v18, v22, v23
	v_cvt_pk_bf16_f32 v19, v24, v25
	v_cvt_pk_bf16_f32 v20, v26, v27
	v_cvt_pk_bf16_f32 v21, v28, v29
	v_max_f32_e32 v11, 0, v0
	v_max_f32_e32 v0, v12, v12
	global_store_dwordx4 v[54:55], v[18:21], off offset:256 nt sc1
	v_pk_mul_f32 v[14:15], v[14:15], v[14:15]
	v_pk_mul_f32 v[16:17], v[16:17], v[16:17]
	v_pk_mul_f32 v[18:19], v[10:11], v[10:11]
	v_max_f32_e32 v10, 0, v0
	v_max_f32_e32 v0, v13, v13
	v_max_f32_e32 v11, 0, v0
	v_max_f32_e32 v0, v6, v6
	v_max_f32_e32 v6, 0, v0
	v_max_f32_e32 v0, v7, v7
	v_max_f32_e32 v7, 0, v0
	v_max_f32_e32 v0, v8, v8
	v_max_f32_e32 v8, 0, v0
	v_max_f32_e32 v0, v9, v9
	v_max_f32_e32 v9, 0, v0
	v_max_f32_e32 v0, v2, v2
	v_pk_mul_f32 v[20:21], v[10:11], v[10:11]
	v_max_f32_e32 v2, 0, v0
	v_max_f32_e32 v0, v3, v3
	v_cvt_pk_bf16_f32 v10, v14, v15
	v_cvt_pk_bf16_f32 v11, v16, v17
	v_cvt_pk_bf16_f32 v12, v18, v19
	v_cvt_pk_bf16_f32 v13, v20, v21
	v_max_f32_e32 v3, 0, v0
	v_max_f32_e32 v0, v4, v4
	global_store_dwordx4 v[46:47], v[10:13], off offset:256 nt sc1
	v_pk_mul_f32 v[6:7], v[6:7], v[6:7]
	v_pk_mul_f32 v[8:9], v[8:9], v[8:9]
	v_pk_mul_f32 v[10:11], v[2:3], v[2:3]
	v_max_f32_e32 v2, 0, v0
	v_max_f32_e32 v0, v5, v5
	v_max_f32_e32 v3, 0, v0
	v_pk_mul_f32 v[12:13], v[2:3], v[2:3]
	v_cvt_pk_bf16_f32 v2, v6, v7
	v_cvt_pk_bf16_f32 v3, v8, v9
	v_cvt_pk_bf16_f32 v4, v10, v11
	v_cvt_pk_bf16_f32 v5, v12, v13
	s_and_b64 vcc, exec, s[12:13]
	s_mov_b32 s14, s15
	s_mov_b32 s16, s7
	global_store_dwordx4 v[38:39], v[2:5], off offset:256 nt sc1
	s_cbranch_vccnz .LBB0_83
